# adds: counted vmcnt at the GEMM unit seam - the peeled first K-step of P3/P4/P5 units no longer waits for the previous unit's epilogue stores (vmcnt 8 -> 8+stores)
# speedup vs baseline: 1.0051x; 1.0034x over previous
.LBB0_677:
	s_ashr_i32 s47, s46, 31
	s_lshl_b64 s[48:49], s[46:47], 21
	s_add_u32 s48, s86, s48
	s_addc_u32 s49, s87, s49
	s_and_b64 s[50:51], s[4:5], exec
	s_cselect_b32 s7, s49, s59
	s_cselect_b32 s47, s48, s58
	s_ashr_i32 s45, s44, 31
	s_lshl_b64 s[50:51], s[44:45], 21
	s_add_u32 s50, s82, s50
	s_addc_u32 s51, s83, s51
	s_and_b64 s[62:63], s[4:5], exec
	s_cselect_b32 s45, s51, s61
	s_cselect_b32 s57, s50, s60
	s_add_u32 s58, s58, 0x100080
	s_addc_u32 s59, s59, 0
	s_add_u32 s76, s60, 0x100
	s_addc_u32 s77, s61, 0
	s_mov_b32 s78, -2
	s_waitcnt lgkmcnt(0)
	ds_read_b128 v[148:151], v159
	ds_read_b128 v[152:155], v159 offset:1024
	ds_read_b128 v[164:167], v159 offset:2048
	ds_read_b128 v[168:171], v159 offset:3072
	ds_read_b128 v[172:175], v160
	ds_read_b128 v[176:179], v160 offset:1024
	ds_read_b128 v[180:183], v160 offset:2048
	ds_read_b128 v[184:187], v160 offset:3072
	s_add_u32 s60, s58, 0xfff00080
	s_addc_u32 s61, s59, -1
	s_cmp_eq_u32 s78, 60
	s_cselect_b32 s63, s7, s61
	s_cselect_b32 s62, s47, s60
	s_cselect_b32 s61, s45, s77
	s_cselect_b32 s60, s57, s76
	s_add_i32 m0, s64, 0xc000
	ds_read_b128 v[188:191], v161
	ds_read_b128 v[192:195], v161 offset:1024
	ds_read_b128 v[198:201], v161 offset:2048
	ds_read_b128 v[202:205], v161 offset:3072
	ds_read_b128 v[206:209], v161 offset:4096
	ds_read_b128 v[210:213], v161 offset:5120
	ds_read_b128 v[214:217], v161 offset:6144
	ds_read_b128 v[218:221], v161 offset:7168
	global_load_lds_dwordx4 v140, s[58:59]
	s_add_i32 m0, s64, 0xe000
	s_nop 0
	global_load_lds_dwordx4 v142, s[58:59]
	s_waitcnt vmcnt(32)
	s_waitcnt lgkmcnt(0)
	s_setprio 1
	s_barrier
	v_mfma_f32_16x16x32_bf16 v[126:129], v[148:151], v[188:191], 0
	v_mfma_f32_16x16x32_bf16 v[122:125], v[164:167], v[188:191], 0
	v_mfma_f32_16x16x32_bf16 v[110:113], v[148:151], v[198:201], 0
	v_mfma_f32_16x16x32_bf16 v[106:109], v[164:167], v[198:201], 0
	v_mfma_f32_16x16x32_bf16 v[94:97], v[148:151], v[206:209], 0
	v_mfma_f32_16x16x32_bf16 v[90:93], v[164:167], v[206:209], 0
	v_mfma_f32_16x16x32_bf16 v[78:81], v[148:151], v[214:217], 0
	v_mfma_f32_16x16x32_bf16 v[74:77], v[164:167], v[214:217], 0
	v_mfma_f32_16x16x32_bf16 v[126:129], v[152:155], v[192:195], v[126:129]
	v_mfma_f32_16x16x32_bf16 v[122:125], v[168:171], v[192:195], v[122:125]
	v_mfma_f32_16x16x32_bf16 v[110:113], v[152:155], v[202:205], v[110:113]
	v_mfma_f32_16x16x32_bf16 v[106:109], v[168:171], v[202:205], v[106:109]
	v_mfma_f32_16x16x32_bf16 v[94:97], v[152:155], v[210:213], v[94:97]
	v_mfma_f32_16x16x32_bf16 v[90:93], v[168:171], v[210:213], v[90:93]
	v_mfma_f32_16x16x32_bf16 v[78:81], v[152:155], v[218:221], v[78:81]
	v_mfma_f32_16x16x32_bf16 v[74:77], v[168:171], v[218:221], v[74:77]
	v_mfma_f32_16x16x32_bf16 v[118:121], v[172:175], v[188:191], 0
	v_mfma_f32_16x16x32_bf16 v[114:117], v[180:183], v[188:191], 0
	v_mfma_f32_16x16x32_bf16 v[102:105], v[172:175], v[198:201], 0
	v_mfma_f32_16x16x32_bf16 v[98:101], v[180:183], v[198:201], 0
	v_mfma_f32_16x16x32_bf16 v[86:89], v[172:175], v[206:209], 0
	v_mfma_f32_16x16x32_bf16 v[82:85], v[180:183], v[206:209], 0
	v_mfma_f32_16x16x32_bf16 v[70:73], v[172:175], v[214:217], 0
	v_mfma_f32_16x16x32_bf16 v[66:69], v[180:183], v[214:217], 0
	v_mfma_f32_16x16x32_bf16 v[118:121], v[176:179], v[192:195], v[118:121]
	v_mfma_f32_16x16x32_bf16 v[114:117], v[184:187], v[192:195], v[114:117]
	v_mfma_f32_16x16x32_bf16 v[102:105], v[176:179], v[202:205], v[102:105]
	v_mfma_f32_16x16x32_bf16 v[98:101], v[184:187], v[202:205], v[98:101]
	v_mfma_f32_16x16x32_bf16 v[86:89], v[176:179], v[210:213], v[86:89]
	v_mfma_f32_16x16x32_bf16 v[82:85], v[184:187], v[210:213], v[82:85]
	v_mfma_f32_16x16x32_bf16 v[70:73], v[176:179], v[218:221], v[70:73]
	v_mfma_f32_16x16x32_bf16 v[66:69], v[184:187], v[218:221], v[66:69]
	s_barrier
	s_setprio 0
	s_add_i32 s79, s74, s33
	s_mov_b32 m0, s79
	ds_read_b128 v[188:191], v161 offset:16384
	ds_read_b128 v[192:195], v161 offset:17408
	ds_read_b128 v[198:201], v161 offset:18432
	ds_read_b128 v[202:205], v161 offset:19456
	ds_read_b128 v[206:209], v161 offset:20480
	ds_read_b128 v[210:213], v161 offset:21504
	ds_read_b128 v[214:217], v161 offset:22528
	ds_read_b128 v[218:221], v161 offset:23552
	global_load_lds_dwordx4 v132, s[60:61]
	s_add_i32 m0, s79, 0x2000
	s_add_u32 s80, s60, 0x100000
	s_addc_u32 s81, s61, 0
	s_add_i32 s79, s75, s33
	global_load_lds_dwordx4 v136, s[60:61]
	s_mov_b32 m0, s79
	global_load_lds_dwordx4 v132, s[80:81]
	s_add_i32 m0, s79, 0x2000
	s_nop 0
	global_load_lds_dwordx4 v136, s[80:81]
	s_mov_b32 m0, s64
	s_nop 0
	global_load_lds_dwordx4 v130, s[62:63]
	s_mov_b32 m0, s65
	s_nop 0
	global_load_lds_dwordx4 v134, s[62:63]
	s_waitcnt vmcnt(32)
	s_waitcnt lgkmcnt(0)
	s_setprio 1
	s_barrier
	v_mfma_f32_16x16x32_bf16 v[62:65], v[148:151], v[188:191], 0
	v_mfma_f32_16x16x32_bf16 v[58:61], v[164:167], v[188:191], 0
	v_mfma_f32_16x16x32_bf16 v[46:49], v[148:151], v[198:201], 0
	v_mfma_f32_16x16x32_bf16 v[42:45], v[164:167], v[198:201], 0
	v_mfma_f32_16x16x32_bf16 v[30:33], v[148:151], v[206:209], 0
	v_mfma_f32_16x16x32_bf16 v[26:29], v[164:167], v[206:209], 0
	v_mfma_f32_16x16x32_bf16 v[14:17], v[148:151], v[214:217], 0
	v_mfma_f32_16x16x32_bf16 v[10:13], v[164:167], v[214:217], 0
	v_mfma_f32_16x16x32_bf16 v[62:65], v[152:155], v[192:195], v[62:65]
	v_mfma_f32_16x16x32_bf16 v[58:61], v[168:171], v[192:195], v[58:61]
	v_mfma_f32_16x16x32_bf16 v[46:49], v[152:155], v[202:205], v[46:49]
	v_mfma_f32_16x16x32_bf16 v[42:45], v[168:171], v[202:205], v[42:45]
	v_mfma_f32_16x16x32_bf16 v[30:33], v[152:155], v[210:213], v[30:33]
	v_mfma_f32_16x16x32_bf16 v[26:29], v[168:171], v[210:213], v[26:29]
	v_mfma_f32_16x16x32_bf16 v[14:17], v[152:155], v[218:221], v[14:17]
	v_mfma_f32_16x16x32_bf16 v[10:13], v[168:171], v[218:221], v[10:13]
	v_mfma_f32_16x16x32_bf16 v[54:57], v[172:175], v[188:191], 0
	v_mfma_f32_16x16x32_bf16 v[50:53], v[180:183], v[188:191], 0
	v_mfma_f32_16x16x32_bf16 v[38:41], v[172:175], v[198:201], 0
	v_mfma_f32_16x16x32_bf16 v[34:37], v[180:183], v[198:201], 0
	v_mfma_f32_16x16x32_bf16 v[22:25], v[172:175], v[206:209], 0
	v_mfma_f32_16x16x32_bf16 v[18:21], v[180:183], v[206:209], 0
	v_mfma_f32_16x16x32_bf16 v[6:9], v[172:175], v[214:217], 0
	v_mfma_f32_16x16x32_bf16 v[2:5], v[180:183], v[214:217], 0
	v_mfma_f32_16x16x32_bf16 v[54:57], v[176:179], v[192:195], v[54:57]
	v_mfma_f32_16x16x32_bf16 v[50:53], v[184:187], v[192:195], v[50:53]
	v_mfma_f32_16x16x32_bf16 v[38:41], v[176:179], v[202:205], v[38:41]
	v_mfma_f32_16x16x32_bf16 v[34:37], v[184:187], v[202:205], v[34:37]
	v_mfma_f32_16x16x32_bf16 v[22:25], v[176:179], v[210:213], v[22:25]
	v_mfma_f32_16x16x32_bf16 v[18:21], v[184:187], v[210:213], v[18:21]
	v_mfma_f32_16x16x32_bf16 v[6:9], v[176:179], v[218:221], v[6:9]
	v_mfma_f32_16x16x32_bf16 v[2:5], v[184:187], v[218:221], v[2:5]
	s_barrier
	s_setprio 0
	s_add_i32 s79, 0, 0x18000
	v_add_u32_e32 v138, s79, v157
	s_add_i32 s80, 0, 0x1c000
	ds_read_b128 v[148:151], v138
	ds_read_b128 v[152:155], v138 offset:1024
	ds_read_b128 v[164:167], v138 offset:2048
	ds_read_b128 v[168:171], v138 offset:3072
	v_add_u32_e32 v138, s80, v157
	ds_read_b128 v[172:175], v138
	ds_read_b128 v[176:179], v138 offset:1024
	ds_read_b128 v[180:183], v138 offset:2048
	ds_read_b128 v[184:187], v138 offset:3072
	s_add_u32 s62, s62, 0x100000
	s_addc_u32 s63, s63, 0
	s_mov_b32 m0, s66
	ds_read_b128 v[188:191], v161 offset:32768
	ds_read_b128 v[192:195], v161 offset:33792
	ds_read_b128 v[198:201], v161 offset:34816
	ds_read_b128 v[202:205], v161 offset:35840
	ds_read_b128 v[206:209], v161 offset:36864
	ds_read_b128 v[210:213], v161 offset:37888
	ds_read_b128 v[214:217], v161 offset:38912
	ds_read_b128 v[218:221], v161 offset:39936
	global_load_lds_dwordx4 v130, s[62:63]
	s_mov_b32 m0, s67
	s_nop 0
	global_load_lds_dwordx4 v134, s[62:63]
	s_waitcnt vmcnt(8)
	s_waitcnt lgkmcnt(0)
	s_setprio 1
	s_barrier
	v_mfma_f32_16x16x32_bf16 v[126:129], v[148:151], v[188:191], v[126:129]
	v_mfma_f32_16x16x32_bf16 v[122:125], v[164:167], v[188:191], v[122:125]
	v_mfma_f32_16x16x32_bf16 v[110:113], v[148:151], v[198:201], v[110:113]
	v_mfma_f32_16x16x32_bf16 v[106:109], v[164:167], v[198:201], v[106:109]
	v_mfma_f32_16x16x32_bf16 v[94:97], v[148:151], v[206:209], v[94:97]
	v_mfma_f32_16x16x32_bf16 v[90:93], v[164:167], v[206:209], v[90:93]
	v_mfma_f32_16x16x32_bf16 v[78:81], v[148:151], v[214:217], v[78:81]
	v_mfma_f32_16x16x32_bf16 v[74:77], v[164:167], v[214:217], v[74:77]
	v_mfma_f32_16x16x32_bf16 v[126:129], v[152:155], v[192:195], v[126:129]
	v_mfma_f32_16x16x32_bf16 v[122:125], v[168:171], v[192:195], v[122:125]
	v_mfma_f32_16x16x32_bf16 v[110:113], v[152:155], v[202:205], v[110:113]
	v_mfma_f32_16x16x32_bf16 v[106:109], v[168:171], v[202:205], v[106:109]
	v_mfma_f32_16x16x32_bf16 v[94:97], v[152:155], v[210:213], v[94:97]
	v_mfma_f32_16x16x32_bf16 v[90:93], v[168:171], v[210:213], v[90:93]
	v_mfma_f32_16x16x32_bf16 v[78:81], v[152:155], v[218:221], v[78:81]
	v_mfma_f32_16x16x32_bf16 v[74:77], v[168:171], v[218:221], v[74:77]
	v_mfma_f32_16x16x32_bf16 v[118:121], v[172:175], v[188:191], v[118:121]
	v_mfma_f32_16x16x32_bf16 v[114:117], v[180:183], v[188:191], v[114:117]
	v_mfma_f32_16x16x32_bf16 v[102:105], v[172:175], v[198:201], v[102:105]
	v_mfma_f32_16x16x32_bf16 v[98:101], v[180:183], v[198:201], v[98:101]
	v_mfma_f32_16x16x32_bf16 v[86:89], v[172:175], v[206:209], v[86:89]
	v_mfma_f32_16x16x32_bf16 v[82:85], v[180:183], v[206:209], v[82:85]
	v_mfma_f32_16x16x32_bf16 v[70:73], v[172:175], v[214:217], v[70:73]
	v_mfma_f32_16x16x32_bf16 v[66:69], v[180:183], v[214:217], v[66:69]
	v_mfma_f32_16x16x32_bf16 v[118:121], v[176:179], v[192:195], v[118:121]
	v_mfma_f32_16x16x32_bf16 v[114:117], v[184:187], v[192:195], v[114:117]
	v_mfma_f32_16x16x32_bf16 v[102:105], v[176:179], v[202:205], v[102:105]
	v_mfma_f32_16x16x32_bf16 v[98:101], v[184:187], v[202:205], v[98:101]
	v_mfma_f32_16x16x32_bf16 v[86:89], v[176:179], v[210:213], v[86:89]
	v_mfma_f32_16x16x32_bf16 v[82:85], v[184:187], v[210:213], v[82:85]
	v_mfma_f32_16x16x32_bf16 v[70:73], v[176:179], v[218:221], v[70:73]
	v_mfma_f32_16x16x32_bf16 v[66:69], v[184:187], v[218:221], v[66:69]
	s_barrier
	s_setprio 0
	s_add_u32 s60, s60, 0x80
	s_addc_u32 s61, s61, 0
	s_add_i32 m0, s33, 0x18000
	ds_read_b128 v[188:191], v161 offset:49152
	ds_read_b128 v[192:195], v161 offset:50176
	ds_read_b128 v[198:201], v161 offset:51200
	ds_read_b128 v[202:205], v161 offset:52224
	ds_read_b128 v[206:209], v161 offset:53248
	ds_read_b128 v[210:213], v161 offset:54272
	ds_read_b128 v[214:217], v161 offset:55296
	ds_read_b128 v[218:221], v161 offset:56320
	global_load_lds_dwordx4 v132, s[60:61]
	s_add_i32 m0, s33, 0x1a000
	s_add_u32 s62, s62, 0xfff00080
	global_load_lds_dwordx4 v136, s[60:61]
	s_addc_u32 s63, s63, -1
	s_add_u32 s60, s60, 0x100000
	s_addc_u32 s61, s61, 0
	s_add_i32 m0, s33, 0x1c000
	s_nop 0
	global_load_lds_dwordx4 v132, s[60:61]
	s_add_i32 m0, s33, 0x1e000
	s_nop 0
	global_load_lds_dwordx4 v136, s[60:61]
	s_mov_b32 m0, s69
	s_nop 0
	global_load_lds_dwordx4 v130, s[62:63]
	s_mov_b32 m0, s70
	s_nop 0
	global_load_lds_dwordx4 v134, s[62:63]
	s_waitcnt vmcnt(8)
	s_waitcnt lgkmcnt(0)
	s_setprio 1
	s_barrier
	v_mfma_f32_16x16x32_bf16 v[62:65], v[148:151], v[188:191], v[62:65]
	v_mfma_f32_16x16x32_bf16 v[58:61], v[164:167], v[188:191], v[58:61]
	v_mfma_f32_16x16x32_bf16 v[46:49], v[148:151], v[198:201], v[46:49]
	v_mfma_f32_16x16x32_bf16 v[42:45], v[164:167], v[198:201], v[42:45]
	v_mfma_f32_16x16x32_bf16 v[30:33], v[148:151], v[206:209], v[30:33]
	v_mfma_f32_16x16x32_bf16 v[26:29], v[164:167], v[206:209], v[26:29]
	v_mfma_f32_16x16x32_bf16 v[14:17], v[148:151], v[214:217], v[14:17]
	v_mfma_f32_16x16x32_bf16 v[10:13], v[164:167], v[214:217], v[10:13]
	v_mfma_f32_16x16x32_bf16 v[62:65], v[152:155], v[192:195], v[62:65]
	v_mfma_f32_16x16x32_bf16 v[58:61], v[168:171], v[192:195], v[58:61]
	v_mfma_f32_16x16x32_bf16 v[46:49], v[152:155], v[202:205], v[46:49]
	v_mfma_f32_16x16x32_bf16 v[42:45], v[168:171], v[202:205], v[42:45]
	v_mfma_f32_16x16x32_bf16 v[30:33], v[152:155], v[210:213], v[30:33]
	v_mfma_f32_16x16x32_bf16 v[26:29], v[168:171], v[210:213], v[26:29]
	v_mfma_f32_16x16x32_bf16 v[14:17], v[152:155], v[218:221], v[14:17]
	v_mfma_f32_16x16x32_bf16 v[10:13], v[168:171], v[218:221], v[10:13]
	v_mfma_f32_16x16x32_bf16 v[54:57], v[172:175], v[188:191], v[54:57]
	v_mfma_f32_16x16x32_bf16 v[50:53], v[180:183], v[188:191], v[50:53]
	v_mfma_f32_16x16x32_bf16 v[38:41], v[172:175], v[198:201], v[38:41]
	v_mfma_f32_16x16x32_bf16 v[34:37], v[180:183], v[198:201], v[34:37]
	v_mfma_f32_16x16x32_bf16 v[22:25], v[172:175], v[206:209], v[22:25]
	v_mfma_f32_16x16x32_bf16 v[18:21], v[180:183], v[206:209], v[18:21]
	v_mfma_f32_16x16x32_bf16 v[6:9], v[172:175], v[214:217], v[6:9]
	v_mfma_f32_16x16x32_bf16 v[2:5], v[180:183], v[214:217], v[2:5]
	v_mfma_f32_16x16x32_bf16 v[54:57], v[176:179], v[192:195], v[54:57]
	v_mfma_f32_16x16x32_bf16 v[50:53], v[184:187], v[192:195], v[50:53]
	v_mfma_f32_16x16x32_bf16 v[38:41], v[176:179], v[202:205], v[38:41]
	v_mfma_f32_16x16x32_bf16 v[34:37], v[184:187], v[202:205], v[34:37]
	v_mfma_f32_16x16x32_bf16 v[22:25], v[176:179], v[210:213], v[22:25]
	v_mfma_f32_16x16x32_bf16 v[18:21], v[184:187], v[210:213], v[18:21]
	v_mfma_f32_16x16x32_bf16 v[6:9], v[176:179], v[218:221], v[6:9]
	v_mfma_f32_16x16x32_bf16 v[2:5], v[184:187], v[218:221], v[2:5]
	s_barrier
	s_setprio 0
	s_add_i32 s78, s78, 2
	s_add_u32 s58, s58, 0x100
	s_addc_u32 s59, s59, 0
	s_add_u32 s76, s76, 0x100
	s_addc_u32 s77, s77, 0
	s_cmp_gt_u32 s78, 61
	.p2align	8

.LBB0_806:
	s_ashr_i32 s35, s34, 31
	s_lshl_b64 s[36:37], s[34:35], 21
	s_add_u32 s36, s8, s36
	s_addc_u32 s37, s9, s37
	s_and_b64 s[38:39], s[0:1], exec
	s_cselect_b32 s35, s37, s43
	s_cselect_b32 s64, s36, s42
	s_ashr_i32 s31, s30, 31
	s_lshl_b64 s[38:39], s[30:31], 21
	s_add_u32 s38, s76, s38
	s_addc_u32 s39, s77, s39
	s_and_b64 s[46:47], s[0:1], exec
	s_cselect_b32 s31, s39, s45
	s_cselect_b32 s65, s38, s44
	s_add_u32 s42, s42, 0x100080
	s_addc_u32 s43, s43, 0
	s_add_u32 s66, s44, 0x100
	s_addc_u32 s67, s45, 0
	s_mov_b32 s68, -2
	ds_read_b128 v[154:157], v150
	ds_read_b128 v[158:161], v150 offset:1024
	ds_read_b128 v[162:165], v150 offset:2048
	ds_read_b128 v[166:169], v150 offset:3072
	ds_read_b128 v[170:173], v151
	ds_read_b128 v[174:177], v151 offset:1024
	ds_read_b128 v[178:181], v151 offset:2048
	ds_read_b128 v[182:185], v151 offset:3072
	s_add_u32 s44, s42, 0xfff00080
	s_addc_u32 s45, s43, -1
	s_cmp_eq_u32 s68, 60
	s_cselect_b32 s47, s35, s45
	s_cselect_b32 s46, s64, s44
	s_cselect_b32 s45, s31, s67
	s_cselect_b32 s44, s65, s66
	s_add_i32 m0, s41, 0xc000
	ds_read_b128 v[186:189], v152
	ds_read_b128 v[190:193], v152 offset:1024
	ds_read_b128 v[198:201], v152 offset:2048
	ds_read_b128 v[202:205], v152 offset:3072
	ds_read_b128 v[206:209], v152 offset:4096
	ds_read_b128 v[210:213], v152 offset:5120
	ds_read_b128 v[214:217], v152 offset:6144
	ds_read_b128 v[218:221], v152 offset:7168
	global_load_lds_dwordx4 v138, s[42:43]
	s_add_i32 m0, s41, 0xe000
	s_nop 0
	global_load_lds_dwordx4 v140, s[42:43]
	s_waitcnt vmcnt(24)
	s_waitcnt lgkmcnt(0)
	s_setprio 1
	s_barrier
	v_mfma_f32_16x16x32_bf16 v[126:129], v[154:157], v[186:189], 0
	v_mfma_f32_16x16x32_bf16 v[122:125], v[162:165], v[186:189], 0
	v_mfma_f32_16x16x32_bf16 v[110:113], v[154:157], v[198:201], 0
	v_mfma_f32_16x16x32_bf16 v[106:109], v[162:165], v[198:201], 0
	v_mfma_f32_16x16x32_bf16 v[94:97], v[154:157], v[206:209], 0
	v_mfma_f32_16x16x32_bf16 v[90:93], v[162:165], v[206:209], 0
	v_mfma_f32_16x16x32_bf16 v[78:81], v[154:157], v[214:217], 0
	v_mfma_f32_16x16x32_bf16 v[74:77], v[162:165], v[214:217], 0
	v_mfma_f32_16x16x32_bf16 v[126:129], v[158:161], v[190:193], v[126:129]
	v_mfma_f32_16x16x32_bf16 v[122:125], v[166:169], v[190:193], v[122:125]
	v_mfma_f32_16x16x32_bf16 v[110:113], v[158:161], v[202:205], v[110:113]
	v_mfma_f32_16x16x32_bf16 v[106:109], v[166:169], v[202:205], v[106:109]
	v_mfma_f32_16x16x32_bf16 v[94:97], v[158:161], v[210:213], v[94:97]
	v_mfma_f32_16x16x32_bf16 v[90:93], v[166:169], v[210:213], v[90:93]
	v_mfma_f32_16x16x32_bf16 v[78:81], v[158:161], v[218:221], v[78:81]
	v_mfma_f32_16x16x32_bf16 v[74:77], v[166:169], v[218:221], v[74:77]
	v_mfma_f32_16x16x32_bf16 v[118:121], v[170:173], v[186:189], 0
	v_mfma_f32_16x16x32_bf16 v[114:117], v[178:181], v[186:189], 0
	v_mfma_f32_16x16x32_bf16 v[102:105], v[170:173], v[198:201], 0
	v_mfma_f32_16x16x32_bf16 v[98:101], v[178:181], v[198:201], 0
	v_mfma_f32_16x16x32_bf16 v[86:89], v[170:173], v[206:209], 0
	v_mfma_f32_16x16x32_bf16 v[82:85], v[178:181], v[206:209], 0
	v_mfma_f32_16x16x32_bf16 v[70:73], v[170:173], v[214:217], 0
	v_mfma_f32_16x16x32_bf16 v[66:69], v[178:181], v[214:217], 0
	v_mfma_f32_16x16x32_bf16 v[118:121], v[174:177], v[190:193], v[118:121]
	v_mfma_f32_16x16x32_bf16 v[114:117], v[182:185], v[190:193], v[114:117]
	v_mfma_f32_16x16x32_bf16 v[102:105], v[174:177], v[202:205], v[102:105]
	v_mfma_f32_16x16x32_bf16 v[98:101], v[182:185], v[202:205], v[98:101]
	v_mfma_f32_16x16x32_bf16 v[86:89], v[174:177], v[210:213], v[86:89]
	v_mfma_f32_16x16x32_bf16 v[82:85], v[182:185], v[210:213], v[82:85]
	v_mfma_f32_16x16x32_bf16 v[70:73], v[174:177], v[218:221], v[70:73]
	v_mfma_f32_16x16x32_bf16 v[66:69], v[182:185], v[218:221], v[66:69]
	s_barrier
	s_setprio 0
	s_add_i32 s69, s57, s33
	s_mov_b32 m0, s69
	ds_read_b128 v[186:189], v152 offset:16384
	ds_read_b128 v[190:193], v152 offset:17408
	ds_read_b128 v[198:201], v152 offset:18432
	ds_read_b128 v[202:205], v152 offset:19456
	ds_read_b128 v[206:209], v152 offset:20480
	ds_read_b128 v[210:213], v152 offset:21504
	ds_read_b128 v[214:217], v152 offset:22528
	ds_read_b128 v[218:221], v152 offset:23552
	global_load_lds_dwordx4 v132, s[44:45]
	s_add_i32 m0, s69, 0x2000
	s_add_u32 s70, s44, 0x100000
	s_addc_u32 s71, s45, 0
	s_add_i32 s69, s58, s33
	global_load_lds_dwordx4 v136, s[44:45]
	s_mov_b32 m0, s69
	global_load_lds_dwordx4 v132, s[70:71]
	s_add_i32 m0, s69, 0x2000
	s_nop 0
	global_load_lds_dwordx4 v136, s[70:71]
	s_mov_b32 m0, s41
	s_nop 0
	global_load_lds_dwordx4 v130, s[46:47]
	s_mov_b32 m0, s50
	s_nop 0
	global_load_lds_dwordx4 v134, s[46:47]
	s_waitcnt vmcnt(24)
	s_waitcnt lgkmcnt(0)
	s_setprio 1
	s_barrier
	v_mfma_f32_16x16x32_bf16 v[62:65], v[154:157], v[186:189], 0
	v_mfma_f32_16x16x32_bf16 v[58:61], v[162:165], v[186:189], 0
	v_mfma_f32_16x16x32_bf16 v[46:49], v[154:157], v[198:201], 0
	v_mfma_f32_16x16x32_bf16 v[42:45], v[162:165], v[198:201], 0
	v_mfma_f32_16x16x32_bf16 v[30:33], v[154:157], v[206:209], 0
	v_mfma_f32_16x16x32_bf16 v[26:29], v[162:165], v[206:209], 0
	v_mfma_f32_16x16x32_bf16 v[14:17], v[154:157], v[214:217], 0
	v_mfma_f32_16x16x32_bf16 v[10:13], v[162:165], v[214:217], 0
	v_mfma_f32_16x16x32_bf16 v[62:65], v[158:161], v[190:193], v[62:65]
	v_mfma_f32_16x16x32_bf16 v[58:61], v[166:169], v[190:193], v[58:61]
	v_mfma_f32_16x16x32_bf16 v[46:49], v[158:161], v[202:205], v[46:49]
	v_mfma_f32_16x16x32_bf16 v[42:45], v[166:169], v[202:205], v[42:45]
	v_mfma_f32_16x16x32_bf16 v[30:33], v[158:161], v[210:213], v[30:33]
	v_mfma_f32_16x16x32_bf16 v[26:29], v[166:169], v[210:213], v[26:29]
	v_mfma_f32_16x16x32_bf16 v[14:17], v[158:161], v[218:221], v[14:17]
	v_mfma_f32_16x16x32_bf16 v[10:13], v[166:169], v[218:221], v[10:13]
	v_mfma_f32_16x16x32_bf16 v[54:57], v[170:173], v[186:189], 0
	v_mfma_f32_16x16x32_bf16 v[50:53], v[178:181], v[186:189], 0
	v_mfma_f32_16x16x32_bf16 v[38:41], v[170:173], v[198:201], 0
	v_mfma_f32_16x16x32_bf16 v[34:37], v[178:181], v[198:201], 0
	v_mfma_f32_16x16x32_bf16 v[22:25], v[170:173], v[206:209], 0
	v_mfma_f32_16x16x32_bf16 v[18:21], v[178:181], v[206:209], 0
	v_mfma_f32_16x16x32_bf16 v[6:9], v[170:173], v[214:217], 0
	v_mfma_f32_16x16x32_bf16 v[2:5], v[178:181], v[214:217], 0
	v_mfma_f32_16x16x32_bf16 v[54:57], v[174:177], v[190:193], v[54:57]
	v_mfma_f32_16x16x32_bf16 v[50:53], v[182:185], v[190:193], v[50:53]
	v_mfma_f32_16x16x32_bf16 v[38:41], v[174:177], v[202:205], v[38:41]
	v_mfma_f32_16x16x32_bf16 v[34:37], v[182:185], v[202:205], v[34:37]
	v_mfma_f32_16x16x32_bf16 v[22:25], v[174:177], v[210:213], v[22:25]
	v_mfma_f32_16x16x32_bf16 v[18:21], v[182:185], v[210:213], v[18:21]
	v_mfma_f32_16x16x32_bf16 v[6:9], v[174:177], v[218:221], v[6:9]
	v_mfma_f32_16x16x32_bf16 v[2:5], v[182:185], v[218:221], v[2:5]
	s_barrier
	s_setprio 0
	s_add_i32 s69, 0, 0x18000
	v_add_u32_e32 v153, s69, v148
	s_add_i32 s70, 0, 0x1c000
	ds_read_b128 v[154:157], v153
	ds_read_b128 v[158:161], v153 offset:1024
	ds_read_b128 v[162:165], v153 offset:2048
	ds_read_b128 v[166:169], v153 offset:3072
	v_add_u32_e32 v153, s70, v148
	ds_read_b128 v[170:173], v153
	ds_read_b128 v[174:177], v153 offset:1024
	ds_read_b128 v[178:181], v153 offset:2048
	ds_read_b128 v[182:185], v153 offset:3072
	s_add_u32 s46, s46, 0x100000
	s_addc_u32 s47, s47, 0
	s_mov_b32 m0, s51
	ds_read_b128 v[186:189], v152 offset:32768
	ds_read_b128 v[190:193], v152 offset:33792
	ds_read_b128 v[198:201], v152 offset:34816
	ds_read_b128 v[202:205], v152 offset:35840
	ds_read_b128 v[206:209], v152 offset:36864
	ds_read_b128 v[210:213], v152 offset:37888
	ds_read_b128 v[214:217], v152 offset:38912
	ds_read_b128 v[218:221], v152 offset:39936
	global_load_lds_dwordx4 v130, s[46:47]
	s_mov_b32 m0, s52
	s_nop 0
	global_load_lds_dwordx4 v134, s[46:47]
	s_waitcnt vmcnt(8)
	s_waitcnt lgkmcnt(0)
	s_setprio 1
	s_barrier
	v_mfma_f32_16x16x32_bf16 v[126:129], v[154:157], v[186:189], v[126:129]
	v_mfma_f32_16x16x32_bf16 v[122:125], v[162:165], v[186:189], v[122:125]
	v_mfma_f32_16x16x32_bf16 v[110:113], v[154:157], v[198:201], v[110:113]
	v_mfma_f32_16x16x32_bf16 v[106:109], v[162:165], v[198:201], v[106:109]
	v_mfma_f32_16x16x32_bf16 v[94:97], v[154:157], v[206:209], v[94:97]
	v_mfma_f32_16x16x32_bf16 v[90:93], v[162:165], v[206:209], v[90:93]
	v_mfma_f32_16x16x32_bf16 v[78:81], v[154:157], v[214:217], v[78:81]
	v_mfma_f32_16x16x32_bf16 v[74:77], v[162:165], v[214:217], v[74:77]
	v_mfma_f32_16x16x32_bf16 v[126:129], v[158:161], v[190:193], v[126:129]
	v_mfma_f32_16x16x32_bf16 v[122:125], v[166:169], v[190:193], v[122:125]
	v_mfma_f32_16x16x32_bf16 v[110:113], v[158:161], v[202:205], v[110:113]
	v_mfma_f32_16x16x32_bf16 v[106:109], v[166:169], v[202:205], v[106:109]
	v_mfma_f32_16x16x32_bf16 v[94:97], v[158:161], v[210:213], v[94:97]
	v_mfma_f32_16x16x32_bf16 v[90:93], v[166:169], v[210:213], v[90:93]
	v_mfma_f32_16x16x32_bf16 v[78:81], v[158:161], v[218:221], v[78:81]
	v_mfma_f32_16x16x32_bf16 v[74:77], v[166:169], v[218:221], v[74:77]
	v_mfma_f32_16x16x32_bf16 v[118:121], v[170:173], v[186:189], v[118:121]
	v_mfma_f32_16x16x32_bf16 v[114:117], v[178:181], v[186:189], v[114:117]
	v_mfma_f32_16x16x32_bf16 v[102:105], v[170:173], v[198:201], v[102:105]
	v_mfma_f32_16x16x32_bf16 v[98:101], v[178:181], v[198:201], v[98:101]
	v_mfma_f32_16x16x32_bf16 v[86:89], v[170:173], v[206:209], v[86:89]
	v_mfma_f32_16x16x32_bf16 v[82:85], v[178:181], v[206:209], v[82:85]
	v_mfma_f32_16x16x32_bf16 v[70:73], v[170:173], v[214:217], v[70:73]
	v_mfma_f32_16x16x32_bf16 v[66:69], v[178:181], v[214:217], v[66:69]
	v_mfma_f32_16x16x32_bf16 v[118:121], v[174:177], v[190:193], v[118:121]
	v_mfma_f32_16x16x32_bf16 v[114:117], v[182:185], v[190:193], v[114:117]
	v_mfma_f32_16x16x32_bf16 v[102:105], v[174:177], v[202:205], v[102:105]
	v_mfma_f32_16x16x32_bf16 v[98:101], v[182:185], v[202:205], v[98:101]
	v_mfma_f32_16x16x32_bf16 v[86:89], v[174:177], v[210:213], v[86:89]
	v_mfma_f32_16x16x32_bf16 v[82:85], v[182:185], v[210:213], v[82:85]
	v_mfma_f32_16x16x32_bf16 v[70:73], v[174:177], v[218:221], v[70:73]
	v_mfma_f32_16x16x32_bf16 v[66:69], v[182:185], v[218:221], v[66:69]
	s_barrier
	s_setprio 0
	s_add_u32 s44, s44, 0x80
	s_addc_u32 s45, s45, 0
	s_add_i32 m0, s33, 0x18000
	ds_read_b128 v[186:189], v152 offset:49152
	ds_read_b128 v[190:193], v152 offset:50176
	ds_read_b128 v[198:201], v152 offset:51200
	ds_read_b128 v[202:205], v152 offset:52224
	ds_read_b128 v[206:209], v152 offset:53248
	ds_read_b128 v[210:213], v152 offset:54272
	ds_read_b128 v[214:217], v152 offset:55296
	ds_read_b128 v[218:221], v152 offset:56320
	global_load_lds_dwordx4 v132, s[44:45]
	s_add_i32 m0, s33, 0x1a000
	s_add_u32 s46, s46, 0xfff00080
	global_load_lds_dwordx4 v136, s[44:45]
	s_addc_u32 s47, s47, -1
	s_add_u32 s44, s44, 0x100000
	s_addc_u32 s45, s45, 0
	s_add_i32 m0, s33, 0x1c000
	s_nop 0
	global_load_lds_dwordx4 v132, s[44:45]
	s_add_i32 m0, s33, 0x1e000
	s_nop 0
	global_load_lds_dwordx4 v136, s[44:45]
	s_mov_b32 m0, s55
	s_nop 0
	global_load_lds_dwordx4 v130, s[46:47]
	s_mov_b32 m0, s56
	s_nop 0
	global_load_lds_dwordx4 v134, s[46:47]
	s_waitcnt vmcnt(8)
	s_waitcnt lgkmcnt(0)
	s_setprio 1
	s_barrier
	v_mfma_f32_16x16x32_bf16 v[62:65], v[154:157], v[186:189], v[62:65]
	v_mfma_f32_16x16x32_bf16 v[58:61], v[162:165], v[186:189], v[58:61]
	v_mfma_f32_16x16x32_bf16 v[46:49], v[154:157], v[198:201], v[46:49]
	v_mfma_f32_16x16x32_bf16 v[42:45], v[162:165], v[198:201], v[42:45]
	v_mfma_f32_16x16x32_bf16 v[30:33], v[154:157], v[206:209], v[30:33]
	v_mfma_f32_16x16x32_bf16 v[26:29], v[162:165], v[206:209], v[26:29]
	v_mfma_f32_16x16x32_bf16 v[14:17], v[154:157], v[214:217], v[14:17]
	v_mfma_f32_16x16x32_bf16 v[10:13], v[162:165], v[214:217], v[10:13]
	v_mfma_f32_16x16x32_bf16 v[62:65], v[158:161], v[190:193], v[62:65]
	v_mfma_f32_16x16x32_bf16 v[58:61], v[166:169], v[190:193], v[58:61]
	v_mfma_f32_16x16x32_bf16 v[46:49], v[158:161], v[202:205], v[46:49]
	v_mfma_f32_16x16x32_bf16 v[42:45], v[166:169], v[202:205], v[42:45]
	v_mfma_f32_16x16x32_bf16 v[30:33], v[158:161], v[210:213], v[30:33]
	v_mfma_f32_16x16x32_bf16 v[26:29], v[166:169], v[210:213], v[26:29]
	v_mfma_f32_16x16x32_bf16 v[14:17], v[158:161], v[218:221], v[14:17]
	v_mfma_f32_16x16x32_bf16 v[10:13], v[166:169], v[218:221], v[10:13]
	v_mfma_f32_16x16x32_bf16 v[54:57], v[170:173], v[186:189], v[54:57]
	v_mfma_f32_16x16x32_bf16 v[50:53], v[178:181], v[186:189], v[50:53]
	v_mfma_f32_16x16x32_bf16 v[38:41], v[170:173], v[198:201], v[38:41]
	v_mfma_f32_16x16x32_bf16 v[34:37], v[178:181], v[198:201], v[34:37]
	v_mfma_f32_16x16x32_bf16 v[22:25], v[170:173], v[206:209], v[22:25]
	v_mfma_f32_16x16x32_bf16 v[18:21], v[178:181], v[206:209], v[18:21]
	v_mfma_f32_16x16x32_bf16 v[6:9], v[170:173], v[214:217], v[6:9]
	v_mfma_f32_16x16x32_bf16 v[2:5], v[178:181], v[214:217], v[2:5]
	v_mfma_f32_16x16x32_bf16 v[54:57], v[174:177], v[190:193], v[54:57]
	v_mfma_f32_16x16x32_bf16 v[50:53], v[182:185], v[190:193], v[50:53]
	v_mfma_f32_16x16x32_bf16 v[38:41], v[174:177], v[202:205], v[38:41]
	v_mfma_f32_16x16x32_bf16 v[34:37], v[182:185], v[202:205], v[34:37]
	v_mfma_f32_16x16x32_bf16 v[22:25], v[174:177], v[210:213], v[22:25]
	v_mfma_f32_16x16x32_bf16 v[18:21], v[182:185], v[210:213], v[18:21]
	v_mfma_f32_16x16x32_bf16 v[6:9], v[174:177], v[218:221], v[6:9]
	v_mfma_f32_16x16x32_bf16 v[2:5], v[182:185], v[218:221], v[2:5]
	s_barrier
	s_setprio 0
	s_add_i32 s68, s68, 2
	s_add_u32 s42, s42, 0x100
	s_addc_u32 s43, s43, 0
	s_add_u32 s66, s66, 0x100
	s_addc_u32 s67, s67, 0
	s_cmp_gt_u32 s68, 61
	.p2align	8

.LBB0_896:
	s_ashr_i32 s35, s34, 31
	s_lshl_b64 s[36:37], s[34:35], 23
	s_add_u32 s36, s86, s36
	s_addc_u32 s37, s87, s37
	s_and_b64 s[38:39], s[0:1], exec
	s_cselect_b32 s35, s37, s43
	s_cselect_b32 s63, s36, s42
	s_ashr_i32 s31, s30, 31
	s_lshl_b64 s[38:39], s[30:31], 23
	s_add_u32 s38, s10, s38
	s_addc_u32 s39, s11, s39
	s_and_b64 s[46:47], s[0:1], exec
	s_cselect_b32 s31, s39, s45
	s_cselect_b32 s64, s38, s44
	s_add_u32 s42, s42, 0x400080
	s_addc_u32 s43, s43, 0
	s_add_u32 s65, s44, 0x100
	s_addc_u32 s66, s45, 0
	s_mov_b32 s67, -2
	ds_read_b128 v[146:149], v156
	ds_read_b128 v[150:153], v156 offset:1024
	ds_read_b128 v[160:163], v156 offset:2048
	ds_read_b128 v[164:167], v156 offset:3072
	ds_read_b128 v[168:171], v157
	ds_read_b128 v[172:175], v157 offset:1024
	ds_read_b128 v[176:179], v157 offset:2048
	ds_read_b128 v[180:183], v157 offset:3072
	s_add_u32 s44, s42, 0xffc00080
	s_addc_u32 s45, s43, -1
	s_cmpk_eq_i32 s67, 0xfc
	s_cselect_b32 s47, s35, s45
	s_cselect_b32 s46, s63, s44
	s_cselect_b32 s45, s31, s66
	s_cselect_b32 s44, s64, s65
	s_add_i32 m0, s41, 0xc000
	ds_read_b128 v[184:187], v158
	ds_read_b128 v[188:191], v158 offset:1024
	ds_read_b128 v[192:195], v158 offset:2048
	ds_read_b128 v[198:201], v158 offset:3072
	ds_read_b128 v[202:205], v158 offset:4096
	ds_read_b128 v[206:209], v158 offset:5120
	ds_read_b128 v[210:213], v158 offset:6144
	ds_read_b128 v[214:217], v158 offset:7168
	global_load_lds_dwordx4 v138, s[42:43]
	s_add_i32 m0, s41, 0xe000
	s_nop 0
	global_load_lds_dwordx4 v140, s[42:43]
	s_waitcnt vmcnt(24)
	s_waitcnt lgkmcnt(0)
	s_setprio 1
	s_barrier
	v_mfma_f32_16x16x32_bf16 v[126:129], v[146:149], v[184:187], 0
	v_mfma_f32_16x16x32_bf16 v[122:125], v[160:163], v[184:187], 0
	v_mfma_f32_16x16x32_bf16 v[110:113], v[146:149], v[192:195], 0
	v_mfma_f32_16x16x32_bf16 v[106:109], v[160:163], v[192:195], 0
	v_mfma_f32_16x16x32_bf16 v[94:97], v[146:149], v[202:205], 0
	v_mfma_f32_16x16x32_bf16 v[90:93], v[160:163], v[202:205], 0
	v_mfma_f32_16x16x32_bf16 v[78:81], v[146:149], v[210:213], 0
	v_mfma_f32_16x16x32_bf16 v[74:77], v[160:163], v[210:213], 0
	v_mfma_f32_16x16x32_bf16 v[126:129], v[150:153], v[188:191], v[126:129]
	v_mfma_f32_16x16x32_bf16 v[122:125], v[164:167], v[188:191], v[122:125]
	v_mfma_f32_16x16x32_bf16 v[110:113], v[150:153], v[198:201], v[110:113]
	v_mfma_f32_16x16x32_bf16 v[106:109], v[164:167], v[198:201], v[106:109]
	v_mfma_f32_16x16x32_bf16 v[94:97], v[150:153], v[206:209], v[94:97]
	v_mfma_f32_16x16x32_bf16 v[90:93], v[164:167], v[206:209], v[90:93]
	v_mfma_f32_16x16x32_bf16 v[78:81], v[150:153], v[214:217], v[78:81]
	v_mfma_f32_16x16x32_bf16 v[74:77], v[164:167], v[214:217], v[74:77]
	v_mfma_f32_16x16x32_bf16 v[118:121], v[168:171], v[184:187], 0
	v_mfma_f32_16x16x32_bf16 v[114:117], v[176:179], v[184:187], 0
	v_mfma_f32_16x16x32_bf16 v[102:105], v[168:171], v[192:195], 0
	v_mfma_f32_16x16x32_bf16 v[98:101], v[176:179], v[192:195], 0
	v_mfma_f32_16x16x32_bf16 v[86:89], v[168:171], v[202:205], 0
	v_mfma_f32_16x16x32_bf16 v[82:85], v[176:179], v[202:205], 0
	v_mfma_f32_16x16x32_bf16 v[70:73], v[168:171], v[210:213], 0
	v_mfma_f32_16x16x32_bf16 v[66:69], v[176:179], v[210:213], 0
	v_mfma_f32_16x16x32_bf16 v[118:121], v[172:175], v[188:191], v[118:121]
	v_mfma_f32_16x16x32_bf16 v[114:117], v[180:183], v[188:191], v[114:117]
	v_mfma_f32_16x16x32_bf16 v[102:105], v[172:175], v[198:201], v[102:105]
	v_mfma_f32_16x16x32_bf16 v[98:101], v[180:183], v[198:201], v[98:101]
	v_mfma_f32_16x16x32_bf16 v[86:89], v[172:175], v[206:209], v[86:89]
	v_mfma_f32_16x16x32_bf16 v[82:85], v[180:183], v[206:209], v[82:85]
	v_mfma_f32_16x16x32_bf16 v[70:73], v[172:175], v[214:217], v[70:73]
	v_mfma_f32_16x16x32_bf16 v[66:69], v[180:183], v[214:217], v[66:69]
	s_barrier
	s_setprio 0
	s_add_i32 s68, s56, s48
	s_mov_b32 m0, s68
	ds_read_b128 v[184:187], v158 offset:16384
	ds_read_b128 v[188:191], v158 offset:17408
	ds_read_b128 v[192:195], v158 offset:18432
	ds_read_b128 v[198:201], v158 offset:19456
	ds_read_b128 v[202:205], v158 offset:20480
	ds_read_b128 v[206:209], v158 offset:21504
	ds_read_b128 v[210:213], v158 offset:22528
	ds_read_b128 v[214:217], v158 offset:23552
	global_load_lds_dwordx4 v132, s[44:45]
	s_add_i32 m0, s68, 0x2000
	s_add_u32 s68, s44, 0x400000
	s_addc_u32 s69, s45, 0
	s_add_i32 s70, s57, s48
	global_load_lds_dwordx4 v136, s[44:45]
	s_mov_b32 m0, s70
	global_load_lds_dwordx4 v132, s[68:69]
	s_add_i32 m0, s70, 0x2000
	s_nop 0
	global_load_lds_dwordx4 v136, s[68:69]
	s_mov_b32 m0, s41
	s_nop 0
	global_load_lds_dwordx4 v130, s[46:47]
	s_mov_b32 m0, s49
	s_nop 0
	global_load_lds_dwordx4 v134, s[46:47]
	s_waitcnt vmcnt(24)
	s_waitcnt lgkmcnt(0)
	s_setprio 1
	s_barrier
	v_mfma_f32_16x16x32_bf16 v[62:65], v[146:149], v[184:187], 0
	v_mfma_f32_16x16x32_bf16 v[58:61], v[160:163], v[184:187], 0
	v_mfma_f32_16x16x32_bf16 v[46:49], v[146:149], v[192:195], 0
	v_mfma_f32_16x16x32_bf16 v[42:45], v[160:163], v[192:195], 0
	v_mfma_f32_16x16x32_bf16 v[30:33], v[146:149], v[202:205], 0
	v_mfma_f32_16x16x32_bf16 v[26:29], v[160:163], v[202:205], 0
	v_mfma_f32_16x16x32_bf16 v[14:17], v[146:149], v[210:213], 0
	v_mfma_f32_16x16x32_bf16 v[10:13], v[160:163], v[210:213], 0
	v_mfma_f32_16x16x32_bf16 v[62:65], v[150:153], v[188:191], v[62:65]
	v_mfma_f32_16x16x32_bf16 v[58:61], v[164:167], v[188:191], v[58:61]
	v_mfma_f32_16x16x32_bf16 v[46:49], v[150:153], v[198:201], v[46:49]
	v_mfma_f32_16x16x32_bf16 v[42:45], v[164:167], v[198:201], v[42:45]
	v_mfma_f32_16x16x32_bf16 v[30:33], v[150:153], v[206:209], v[30:33]
	v_mfma_f32_16x16x32_bf16 v[26:29], v[164:167], v[206:209], v[26:29]
	v_mfma_f32_16x16x32_bf16 v[14:17], v[150:153], v[214:217], v[14:17]
	v_mfma_f32_16x16x32_bf16 v[10:13], v[164:167], v[214:217], v[10:13]
	v_mfma_f32_16x16x32_bf16 v[54:57], v[168:171], v[184:187], 0
	v_mfma_f32_16x16x32_bf16 v[50:53], v[176:179], v[184:187], 0
	v_mfma_f32_16x16x32_bf16 v[38:41], v[168:171], v[192:195], 0
	v_mfma_f32_16x16x32_bf16 v[34:37], v[176:179], v[192:195], 0
	v_mfma_f32_16x16x32_bf16 v[22:25], v[168:171], v[202:205], 0
	v_mfma_f32_16x16x32_bf16 v[18:21], v[176:179], v[202:205], 0
	v_mfma_f32_16x16x32_bf16 v[6:9], v[168:171], v[210:213], 0
	v_mfma_f32_16x16x32_bf16 v[2:5], v[176:179], v[210:213], 0
	v_mfma_f32_16x16x32_bf16 v[54:57], v[172:175], v[188:191], v[54:57]
	v_mfma_f32_16x16x32_bf16 v[50:53], v[180:183], v[188:191], v[50:53]
	v_mfma_f32_16x16x32_bf16 v[38:41], v[172:175], v[198:201], v[38:41]
	v_mfma_f32_16x16x32_bf16 v[34:37], v[180:183], v[198:201], v[34:37]
	v_mfma_f32_16x16x32_bf16 v[22:25], v[172:175], v[206:209], v[22:25]
	v_mfma_f32_16x16x32_bf16 v[18:21], v[180:183], v[206:209], v[18:21]
	v_mfma_f32_16x16x32_bf16 v[6:9], v[172:175], v[214:217], v[6:9]
	v_mfma_f32_16x16x32_bf16 v[2:5], v[180:183], v[214:217], v[2:5]
	s_barrier
	s_setprio 0
	s_add_i32 s68, 0, 0x18000
	s_add_i32 s69, 0, 0x1c000
	v_add_u32_e32 v164, s68, v154
	v_add_u32_e32 v180, s69, v154
	ds_read_b128 v[146:149], v164
	ds_read_b128 v[150:153], v164 offset:1024
	ds_read_b128 v[160:163], v164 offset:2048
	ds_read_b128 v[164:167], v164 offset:3072
	ds_read_b128 v[168:171], v180
	ds_read_b128 v[172:175], v180 offset:1024
	ds_read_b128 v[176:179], v180 offset:2048
	ds_read_b128 v[180:183], v180 offset:3072
	s_add_u32 s46, s46, 0x400000
	s_addc_u32 s47, s47, 0
	s_mov_b32 m0, s50
	ds_read_b128 v[184:187], v158 offset:32768
	ds_read_b128 v[188:191], v158 offset:33792
	ds_read_b128 v[192:195], v158 offset:34816
	ds_read_b128 v[198:201], v158 offset:35840
	ds_read_b128 v[202:205], v158 offset:36864
	ds_read_b128 v[206:209], v158 offset:37888
	ds_read_b128 v[210:213], v158 offset:38912
	ds_read_b128 v[214:217], v158 offset:39936
	global_load_lds_dwordx4 v130, s[46:47]
	s_mov_b32 m0, s51
	s_nop 0
	global_load_lds_dwordx4 v134, s[46:47]
	s_waitcnt vmcnt(8)
	s_waitcnt lgkmcnt(0)
	s_setprio 1
	s_barrier
	v_mfma_f32_16x16x32_bf16 v[126:129], v[146:149], v[184:187], v[126:129]
	v_mfma_f32_16x16x32_bf16 v[122:125], v[160:163], v[184:187], v[122:125]
	v_mfma_f32_16x16x32_bf16 v[110:113], v[146:149], v[192:195], v[110:113]
	v_mfma_f32_16x16x32_bf16 v[106:109], v[160:163], v[192:195], v[106:109]
	v_mfma_f32_16x16x32_bf16 v[94:97], v[146:149], v[202:205], v[94:97]
	v_mfma_f32_16x16x32_bf16 v[90:93], v[160:163], v[202:205], v[90:93]
	v_mfma_f32_16x16x32_bf16 v[78:81], v[146:149], v[210:213], v[78:81]
	v_mfma_f32_16x16x32_bf16 v[74:77], v[160:163], v[210:213], v[74:77]
	v_mfma_f32_16x16x32_bf16 v[126:129], v[150:153], v[188:191], v[126:129]
	v_mfma_f32_16x16x32_bf16 v[122:125], v[164:167], v[188:191], v[122:125]
	v_mfma_f32_16x16x32_bf16 v[110:113], v[150:153], v[198:201], v[110:113]
	v_mfma_f32_16x16x32_bf16 v[106:109], v[164:167], v[198:201], v[106:109]
	v_mfma_f32_16x16x32_bf16 v[94:97], v[150:153], v[206:209], v[94:97]
	v_mfma_f32_16x16x32_bf16 v[90:93], v[164:167], v[206:209], v[90:93]
	v_mfma_f32_16x16x32_bf16 v[78:81], v[150:153], v[214:217], v[78:81]
	v_mfma_f32_16x16x32_bf16 v[74:77], v[164:167], v[214:217], v[74:77]
	v_mfma_f32_16x16x32_bf16 v[118:121], v[168:171], v[184:187], v[118:121]
	v_mfma_f32_16x16x32_bf16 v[114:117], v[176:179], v[184:187], v[114:117]
	v_mfma_f32_16x16x32_bf16 v[102:105], v[168:171], v[192:195], v[102:105]
	v_mfma_f32_16x16x32_bf16 v[98:101], v[176:179], v[192:195], v[98:101]
	v_mfma_f32_16x16x32_bf16 v[86:89], v[168:171], v[202:205], v[86:89]
	v_mfma_f32_16x16x32_bf16 v[82:85], v[176:179], v[202:205], v[82:85]
	v_mfma_f32_16x16x32_bf16 v[70:73], v[168:171], v[210:213], v[70:73]
	v_mfma_f32_16x16x32_bf16 v[66:69], v[176:179], v[210:213], v[66:69]
	v_mfma_f32_16x16x32_bf16 v[118:121], v[172:175], v[188:191], v[118:121]
	v_mfma_f32_16x16x32_bf16 v[114:117], v[180:183], v[188:191], v[114:117]
	v_mfma_f32_16x16x32_bf16 v[102:105], v[172:175], v[198:201], v[102:105]
	v_mfma_f32_16x16x32_bf16 v[98:101], v[180:183], v[198:201], v[98:101]
	v_mfma_f32_16x16x32_bf16 v[86:89], v[172:175], v[206:209], v[86:89]
	v_mfma_f32_16x16x32_bf16 v[82:85], v[180:183], v[206:209], v[82:85]
	v_mfma_f32_16x16x32_bf16 v[70:73], v[172:175], v[214:217], v[70:73]
	v_mfma_f32_16x16x32_bf16 v[66:69], v[180:183], v[214:217], v[66:69]
	s_barrier
	s_setprio 0
	s_add_u32 s44, s44, 0x80
	s_addc_u32 s45, s45, 0
	s_add_i32 m0, s48, 0x18000
	ds_read_b128 v[184:187], v158 offset:49152
	ds_read_b128 v[188:191], v158 offset:50176
	ds_read_b128 v[192:195], v158 offset:51200
	ds_read_b128 v[198:201], v158 offset:52224
	ds_read_b128 v[202:205], v158 offset:53248
	ds_read_b128 v[206:209], v158 offset:54272
	ds_read_b128 v[210:213], v158 offset:55296
	ds_read_b128 v[214:217], v158 offset:56320
	global_load_lds_dwordx4 v132, s[44:45]
	s_add_i32 m0, s48, 0x1a000
	s_add_u32 s46, s46, 0xffc00080
	global_load_lds_dwordx4 v136, s[44:45]
	s_addc_u32 s47, s47, -1
	s_add_u32 s44, s44, 0x400000
	s_addc_u32 s45, s45, 0
	s_add_i32 m0, s48, 0x1c000
	s_nop 0
	global_load_lds_dwordx4 v132, s[44:45]
	s_add_i32 m0, s48, 0x1e000
	s_nop 0
	global_load_lds_dwordx4 v136, s[44:45]
	s_mov_b32 m0, s53
	s_nop 0
	global_load_lds_dwordx4 v130, s[46:47]
	s_mov_b32 m0, s54
	s_nop 0
	global_load_lds_dwordx4 v134, s[46:47]
	s_waitcnt vmcnt(8)
	s_waitcnt lgkmcnt(0)
	s_setprio 1
	s_barrier
	v_mfma_f32_16x16x32_bf16 v[62:65], v[146:149], v[184:187], v[62:65]
	v_mfma_f32_16x16x32_bf16 v[58:61], v[160:163], v[184:187], v[58:61]
	v_mfma_f32_16x16x32_bf16 v[46:49], v[146:149], v[192:195], v[46:49]
	v_mfma_f32_16x16x32_bf16 v[42:45], v[160:163], v[192:195], v[42:45]
	v_mfma_f32_16x16x32_bf16 v[30:33], v[146:149], v[202:205], v[30:33]
	v_mfma_f32_16x16x32_bf16 v[26:29], v[160:163], v[202:205], v[26:29]
	v_mfma_f32_16x16x32_bf16 v[14:17], v[146:149], v[210:213], v[14:17]
	v_mfma_f32_16x16x32_bf16 v[10:13], v[160:163], v[210:213], v[10:13]
	v_mfma_f32_16x16x32_bf16 v[62:65], v[150:153], v[188:191], v[62:65]
	v_mfma_f32_16x16x32_bf16 v[58:61], v[164:167], v[188:191], v[58:61]
	v_mfma_f32_16x16x32_bf16 v[46:49], v[150:153], v[198:201], v[46:49]
	v_mfma_f32_16x16x32_bf16 v[42:45], v[164:167], v[198:201], v[42:45]
	v_mfma_f32_16x16x32_bf16 v[30:33], v[150:153], v[206:209], v[30:33]
	v_mfma_f32_16x16x32_bf16 v[26:29], v[164:167], v[206:209], v[26:29]
	v_mfma_f32_16x16x32_bf16 v[14:17], v[150:153], v[214:217], v[14:17]
	v_mfma_f32_16x16x32_bf16 v[10:13], v[164:167], v[214:217], v[10:13]
	v_mfma_f32_16x16x32_bf16 v[54:57], v[168:171], v[184:187], v[54:57]
	v_mfma_f32_16x16x32_bf16 v[50:53], v[176:179], v[184:187], v[50:53]
	v_mfma_f32_16x16x32_bf16 v[38:41], v[168:171], v[192:195], v[38:41]
	v_mfma_f32_16x16x32_bf16 v[34:37], v[176:179], v[192:195], v[34:37]
	v_mfma_f32_16x16x32_bf16 v[22:25], v[168:171], v[202:205], v[22:25]
	v_mfma_f32_16x16x32_bf16 v[18:21], v[176:179], v[202:205], v[18:21]
	v_mfma_f32_16x16x32_bf16 v[6:9], v[168:171], v[210:213], v[6:9]
	v_mfma_f32_16x16x32_bf16 v[2:5], v[176:179], v[210:213], v[2:5]
	v_mfma_f32_16x16x32_bf16 v[54:57], v[172:175], v[188:191], v[54:57]
	v_mfma_f32_16x16x32_bf16 v[50:53], v[180:183], v[188:191], v[50:53]
	v_mfma_f32_16x16x32_bf16 v[38:41], v[172:175], v[198:201], v[38:41]
	v_mfma_f32_16x16x32_bf16 v[34:37], v[180:183], v[198:201], v[34:37]
	v_mfma_f32_16x16x32_bf16 v[22:25], v[172:175], v[206:209], v[22:25]
	v_mfma_f32_16x16x32_bf16 v[18:21], v[180:183], v[206:209], v[18:21]
	v_mfma_f32_16x16x32_bf16 v[6:9], v[172:175], v[214:217], v[6:9]
	v_mfma_f32_16x16x32_bf16 v[2:5], v[180:183], v[214:217], v[2:5]
	s_barrier
	s_setprio 0
	s_add_i32 s67, s67, 2
	s_add_u32 s42, s42, 0x100
	s_addc_u32 s43, s43, 0
	s_add_u32 s65, s65, 0x100
	s_addc_u32 s66, s66, 0
	s_cmpk_gt_u32 s67, 0xfd
	.p2align	8
